# GLA unit (L=2048 path): lane-per-token loads of log-decay/q/k replaced by swizzled LDS-DMA staging one chunk ahead, staged reads at loop top and peeled last chunk
# speedup vs baseline: 1.0164x; 1.0112x over previous
; #define LAS __attribute__((address_space(3)))
; __device__ __forceinline__ int otid() { int t = threadIdx.x; asm volatile("" : "+v"(t)); return t; }
; __device__ __forceinline__ unsigned pk2(float lo, float hi) { f32x2 f = {lo, hi}; bf16x2_t v = __builtin_convertvector(f, bf16x2_t); return __builtin_bit_cast(unsigned, v); }
; __device__ __forceinline__ void gla_unit(LAS unsigned char* lds, const Params& P, const MixBufs& B, float* segst, int layer, int L, int seq, int h, int d, int seg, bool state_only) {
;     ...
;     const int tid = otid(), w = tid >> 6, lane = tid & 63, r = lane & 15, q = lane >> 4;
;     LAS bf16_t* Qa = (LAS bf16_t*)(lds + C::QA); LAS bf16_t* Ka = (LAS bf16_t*)(lds + C::KA); LAS bf16_t* KbT = (LAS bf16_t*)(lds + C::KBT);
;     LAS bf16_t* VT = (LAS bf16_t*)(lds + C::VT); LAS bf16_t* Sc = (LAS bf16_t*)(lds + C::SC); LAS bf16_t* StT = (LAS bf16_t*)(lds + C::STT);
;     LAS float* dstate = (LAS float*)(lds + C::FA);
;     const int base = seq * L, cbeg = seg * 32, cend = cbeg + 32;
;     __syncthreads();
;     f32x4 st = (f32x4){0.f, 0.f, 0.f, 0.f};
;     const int row = tid >> 3, part = tid & 7;
;     const int tm = w >> 1, tn0 = (w & 1) * 2;
;     const int tk = w >> 2, tv = w & 3;
;     const int kidx = 16 + h * 2 + d;
;     if (!state_only) {
;         for (int ps = 0; ps < seg; ++ps) {
;             const float* sp = segst + (size_t)((seq * 8 + ps) * 24 + kidx) * 8256;
; #pragma unroll
;             for (int jj = 0; jj < 4; ++jj) st[jj] = st[jj] * __expf(sp[8192 + tk * 16 + q * 4 + jj]) + sp[jj * 512 + tid];
;         }
;         { u32x2 o; o.x = pk2(st[0], st[1]); o.y = pk2(st[2], st[3]); *(LAS u32x2*)(StT + (tv * 16 + r) * C::LQ + tk * 16 + q * 4) = o; }
;     }
;     float blsum[4] = {0.f, 0.f, 0.f, 0.f};
;     const float* la = B.gla_la + (size_t)d * TG * 128;
;     bf16_t* oout = B.gla_o + (size_t)d * TG * 256;
;     const float qscale = 0.17677669529663687f;
;     f32x4 lv; u32x2 qr, kr; u32x4 x0;
;     ...
;     GLA_LOAD(cbeg);
.LBB0_1357:
	s_and_b64 vcc, exec, s[0:1]
	s_cbranch_vccz .LBB0_1385
	v_readlane_b32 s4, v251, 55
	v_readlane_b32 s5, v251, 56
	s_mov_b64 s[0:1], -1
	s_and_b64 vcc, exec, s[4:5]
	s_cbranch_vccz .LBB0_1378
	s_waitcnt vmcnt(2)
	v_mov_b32_e32 v30, v203
	v_readlane_b32 s2, v251, 57
	v_ashrrev_i32_e32 v22, 6, v30
	v_and_b32_e32 v26, 15, v30
	v_lshlrev_b32_e32 v0, 1, v22
	s_waitcnt vmcnt(1)
	v_and_b32_e32 v36, 3, v22
	v_and_b32_e32 v29, 2, v0
	v_ashrrev_i32_e32 v35, 8, v30
	v_lshl_or_b32 v0, v36, 4, v26
	v_bfe_u32 v27, v30, 4, 2
	v_mul_u32_u24_e32 v0, 0x50, v0
	v_lshlrev_b32_e32 v2, 5, v35
	v_and_b32_e32 v31, 63, v30
	v_add3_u32 v0, 0, v0, v2
	v_lshlrev_b32_e32 v2, 3, v27
	v_readlane_b32 s4, v251, 63
	v_add_u32_e32 v23, v0, v2
	v_or_b32_e32 v0, s2, v31
	v_xad_u32 v2, v31, -1, s4
	v_cndmask_b32_e64 v0, v2, v0, s[76:77]
	v_readlane_b32 s6, v249, 0
	v_lshlrev_b32_e32 v4, 2, v22
	v_readlane_b32 s40, v248, 15
	v_lshlrev_b64 v[2:3], 9, v[0:1]
	v_readlane_b32 s7, v249, 1
	v_ashrrev_i32_e32 v5, 31, v4
	v_readlane_b32 s41, v248, 16
	v_ashrrev_i32_e32 v32, 3, v30
	v_lshl_add_u64 v[2:3], s[6:7], 0, v[2:3]
	v_lshlrev_b64 v[14:15], 2, v[4:5]
	v_mov_b64_e32 v[6:7], s[40:41]
	s_waitcnt lgkmcnt(0)
	s_barrier
	ds_write_b64 v23, v[220:221] offset:33280
	v_lshl_add_u64 v[2:3], v[2:3], 0, v[14:15]
	v_mad_u64_u32 v[6:7], s[0:1], v0, s65, v[6:7]
	v_lshlrev_b64 v[16:17], 1, v[4:5]
	v_xad_u32 v0, v32, -1, s4
	v_readlane_b32 s4, v248, 17
	v_lshl_add_u64 v[6:7], v[6:7], 0, v[16:17]
	s_waitcnt vmcnt(0)
	v_add_u32_e32 v2, s2, v32
	v_readlane_b32 s5, v248, 18
	v_lshlrev_b32_e32 v5, 3, v30
	v_cndmask_b32_e64 v0, v0, v2, s[76:77]
	v_mov_b64_e32 v[2:3], s[4:5]
	v_and_b32_e32 v37, 56, v5
	v_mad_i64_i32 v[2:3], s[0:1], v0, s65, v[2:3]
	v_lshlrev_b32_e32 v0, 1, v37
	v_lshl_add_u64 v[2:3], v[2:3], 0, v[0:1]
	s_nop 0
	global_load_dwordx4 v[6:9], v[2:3], off offset:512
	v_ashrrev_i32_e32 v28, 7, v30
	v_lshl_or_b32 v33, v28, 4, v26
	v_lshl_add_u32 v3, v31, 1, 0
	v_mul_u32_u24_e32 v2, 0x4e, v31
	v_lshlrev_b32_e32 v20, 3, v22
	s_movk_i32 s0, 0x500
	v_mul_lo_u32 v38, v33, s90
	v_add3_u32 v34, v3, v2, v20
	v_bitop3_b32 v2, v5, v32, 56 bitop3:0x6c
	v_lshl_add_u64 v[20:21], s[6:7], 0, v[14:15]
	v_mul_lo_u32 v5, v28, s0
	v_mul_u32_u24_e32 v14, 40, v26
	v_add_u32_e32 v41, 0, v38
	v_mul_u32_u24_e32 v38, 0x48, v26
	v_add_u32_e32 v5, 0, v5
	v_lshlrev_b32_e32 v14, 1, v14
	v_lshlrev_b32_e32 v28, 10, v28
	v_lshlrev_b32_e32 v38, 1, v38
	v_add_u32_e32 v15, v5, v14
	v_bfe_u32 v42, v30, 3, 1
	v_add3_u32 v45, v5, v28, v38
	v_lshlrev_b32_e32 v5, 6, v26
	v_lshl_add_u32 v46, v35, 6, 0
	v_mul_i32_i24_e32 v28, 0x8c0, v35
	v_mul_u32_u24_e32 v35, 0x900, v36
	v_lshlrev_b32_e32 v36, 1, v36
	v_mul_u32_u24_e32 v26, 0x90, v26
	v_add3_u32 v47, v46, v28, v26
	v_add3_u32 v57, 0, v35, v26
	v_bitop3_b32 v26, v36, v27, v42 bitop3:0x36
	v_lshlrev_b32_e32 v58, 4, v26
	v_or_b32_e32 v26, 4, v27
	s_movk_i32 s0, 0x240
	v_or_b32_e32 v4, 1, v4
	v_add_u32_e32 v39, 0, v14
	v_lshlrev_b32_e32 v14, 2, v27
	v_bitop3_b32 v28, v36, v26, v42 bitop3:0x36
	v_mul_lo_u32 v35, v22, s0
	v_lshl_add_u32 v43, v22, 4, 0
	v_mul_lo_u32 v36, v4, s90
	v_mul_u32_u24_e32 v4, 0x90, v37
	v_lshlrev_b32_e32 v2, 1, v2
	v_lshlrev_b32_e32 v22, 4, v29
	v_add3_u32 v37, 0, v4, v2
	v_or_b32_e32 v2, v22, v14
	v_cmp_ge_i32_e32 vcc, v33, v2
	v_lshlrev_b32_e32 v59, 4, v28
	v_readlane_b32 s2, v249, 4
	v_cndmask_b32_e64 v4, 0, 1, vcc
	v_cmp_gt_i32_e32 vcc, v33, v2
	v_lshl_add_u32 v38, v2, 1, v41
	v_mul_u32_u24_e32 v60, 0x500, v29
	v_cndmask_b32_e64 v28, 0, 1, vcc
	v_cndmask_b32_e64 v4, v28, v4, s[76:77]
	v_and_b32_e32 v4, 1, v4
	v_cmp_eq_u32_e32 vcc, 1, v4
	v_or_b32_e32 v4, s2, v2
	v_cmp_gt_i32_e64 s[42:43], v33, v4
	v_or_b32_e32 v4, 2, v2
	v_cmp_ge_i32_e64 s[0:1], v33, v4
	v_and_b32_e32 v44, 48, v30
	v_add_u32_e32 v40, v39, v44
	v_cndmask_b32_e64 v28, 0, 1, s[0:1]
	v_cmp_gt_i32_e64 s[0:1], v33, v4
	v_cmp_eq_u32_e64 s[56:57], 63, v31
	v_lshlrev_b32_e32 v49, 4, v26
	v_cndmask_b32_e64 v4, 0, 1, s[0:1]
	v_cndmask_b32_e64 v4, v4, v28, s[76:77]
	v_and_b32_e32 v4, 1, v4
	v_cmp_eq_u32_e64 s[44:45], 1, v4
	v_or_b32_e32 v4, 3, v2
	v_cmp_ge_i32_e64 s[0:1], v33, v4
	v_or_b32_e32 v2, 1, v29
	v_sub_u32_e32 v51, 0xffff87bf, v32
	v_cndmask_b32_e64 v28, 0, 1, s[0:1]
	v_cmp_gt_i32_e64 s[0:1], v33, v4
	v_add_u32_e32 v52, 0xffff8040, v32
	s_waitcnt vmcnt(4)
; __device__ __forceinline__ void gla_unit(LAS unsigned char* lds, const Params& P, const MixBufs& B, float* segst, int layer, int L, int seq, int h, int d, int seg, bool state_only) {
;     ...
;     GLA_LOAD(cbeg);
;     ...
;             const int i = tm * 16 + r, j0 = tn * 16 + q * 4;
;             float v[4];
; #pragma unroll
;             for (int jj = 0; jj < 4; ++jj) { const int j = j0 + jj; const bool on = d == 0 ? (i >= j) : (i > j); v[jj] = on ? s[jj] : 0.f; }
	v_or_b32_e32 v54, 0xffff8040, v31
	v_cndmask_b32_e64 v4, 0, 1, s[0:1]
	v_cndmask_b32_e64 v4, v4, v28, s[76:77]
	v_and_b32_e32 v4, 1, v4
	v_cmp_eq_u32_e64 s[50:51], 1, v4
	v_lshlrev_b32_e32 v4, 4, v2
	v_or_b32_e32 v28, v4, v14
	v_cmp_ge_i32_e64 s[0:1], v33, v28
	v_lshl_add_u32 v41, v28, 1, v41
	v_lshlrev_b32_e32 v2, 1, v2
	v_cndmask_b32_e64 v48, 0, 1, s[0:1]
	v_cmp_gt_i32_e64 s[0:1], v33, v28
	v_add_u32_e32 v55, 0xffff8000, v33
	v_sub_u32_e32 v56, 0xffff87ff, v33
	v_cndmask_b32_e64 v50, 0, 1, s[0:1]
	v_cndmask_b32_e64 v48, v50, v48, s[76:77]
	v_and_b32_e32 v48, 1, v48
	v_cmp_eq_u32_e64 s[46:47], 1, v48
	v_or_b32_e32 v48, s2, v28
	v_cmp_gt_i32_e64 s[48:49], v33, v48
	v_or_b32_e32 v48, 2, v28
	v_cmp_ge_i32_e64 s[0:1], v33, v48
	s_mov_b32 s2, 31
	v_lshlrev_b32_e32 v14, 1, v14
	v_cndmask_b32_e64 v50, 0, 1, s[0:1]
	v_cmp_gt_i32_e64 s[0:1], v33, v48
	v_add_u32_e32 v32, v40, v60
	v_add_u32_e32 v31, v57, v58
	v_cndmask_b32_e64 v48, 0, 1, s[0:1]
	v_cndmask_b32_e64 v48, v48, v50, s[76:77]
	v_and_b32_e32 v48, 1, v48
	v_cmp_eq_u32_e64 s[52:53], 1, v48
	v_or_b32_e32 v48, 3, v28
	v_cmp_ge_i32_e64 s[0:1], v33, v48
	v_mul_u32_u24_e32 v28, 0x900, v29
	v_lshlrev_b32_e32 v29, 1, v29
	v_cndmask_b32_e64 v50, 0, 1, s[0:1]
	v_cmp_gt_i32_e64 s[0:1], v33, v48
	v_add3_u32 v5, v39, v5, v28
	v_bitop3_b32 v28, v29, v27, v42 bitop3:0x36
	v_cndmask_b32_e64 v48, 0, 1, s[0:1]
	v_cndmask_b32_e64 v48, v48, v50, s[76:77]
	v_lshlrev_b32_e32 v61, 4, v28
	v_bitop3_b32 v28, v29, v26, v42 bitop3:0x36
	v_bitop3_b32 v27, v2, v27, v42 bitop3:0x36
	v_bitop3_b32 v2, v2, v26, v42 bitop3:0x36
	v_and_b32_e32 v48, 1, v48
	v_lshlrev_b32_e32 v62, 4, v28
	v_add_u32_e32 v63, 0x900, v5
	v_lshlrev_b32_e32 v64, 4, v27
	v_lshlrev_b32_e32 v65, 4, v2
	s_movk_i32 s0, 0x87bf
	v_mov_b32_e32 v2, 0
	v_cmp_eq_u32_e64 s[54:55], 1, v48
	v_lshl_add_u64 v[26:27], s[40:41], 0, v[16:17]
	v_lshl_add_u64 v[28:29], s[4:5], 0, v[0:1]
	v_bitop3_b32 v53, v30, s0, 63 bitop3:0x6c
	v_lshlrev_b32_e32 v16, 1, v4
	v_add_u32_e32 v50, v3, v35
	v_add_u32_e32 v48, v3, v36
	v_add_u32_e32 v39, v15, v44
	v_add_u32_e32 v42, v5, v61
	v_add_u32_e32 v40, v5, v62
	v_add_u32_e32 v36, v63, v64
	v_add_u32_e32 v35, v63, v65
	v_add_u32_e32 v30, v57, v59
	v_mov_b32_e32 v3, v2
	v_mov_b32_e32 v4, v2
	v_mov_b32_e32 v5, v2
	v_writelane_b32 v246, s0, 41
	v_writelane_b32 v246, s1, 42
	v_writelane_b32 v246, s6, 43
	v_writelane_b32 v246, s7, 44
	v_writelane_b32 v246, s8, 45
	v_writelane_b32 v246, s9, 46
	v_writelane_b32 v246, s10, 47
	v_writelane_b32 v246, s11, 48
	v_readlane_b32 s0, v249, 0
	v_readlane_b32 s1, v249, 1
	v_readlane_b32 s6, v248, 15
	v_readlane_b32 s7, v248, 16
	v_readlane_b32 s8, v251, 57
	v_readlane_b32 s9, v251, 63
	v_and_b32_e32 v184, 63, v203
	v_lshrrev_b32_e32 v185, 6, v203
	v_mov_b32_e32 v191, 0
	s_add_i32 s9, s9, -1
	v_readfirstlane_b32 s11, v185
	v_lshrrev_b32_e32 v186, 3, v184
	v_and_b32_e32 v187, 7, v184
	v_xor_b32_e32 v187, v187, v186
	v_lshl_or_b32 v186, v185, 3, v186
	v_add_u32_e32 v188, s8, v186
	v_sub_u32_e32 v189, s9, v186
	v_cndmask_b32_e64 v188, v189, v188, s[76:77]
	v_ashrrev_i32_e32 v189, 31, v188
	v_lshlrev_b64 v[188:189], 9, v[188:189]
	v_lshlrev_b32_e32 v190, 4, v187
	v_lshl_add_u64 v[174:175], s[0:1], 0, v[188:189]
	v_lshl_add_u64 v[174:175], v[174:175], 0, v[190:191]
	v_lshrrev_b32_e32 v186, 2, v184
	v_and_b32_e32 v187, 3, v184
	v_and_b32_e32 v192, 3, v186
	v_xor_b32_e32 v187, v187, v192
	v_and_b32_e32 v192, 3, v185
	v_lshl_or_b32 v186, v192, 4, v186
	v_add_u32_e32 v193, s8, v186
	v_sub_u32_e32 v189, s9, v186
	v_cndmask_b32_e64 v193, v189, v193, s[76:77]
	s_nop 0
	v_mad_i64_i32 v[194:195], s[8:9], v193, s65, 0
	v_lshlrev_b32_e32 v190, 4, v187
	v_lshrrev_b32_e32 v192, 2, v185
	v_lshl_or_b32 v190, v192, 8, v190
	v_lshl_add_u64 v[176:177], s[6:7], 0, v[194:195]
	v_lshl_add_u64 v[176:177], v[176:177], 0, v[190:191]
	v_mov_b32_e32 v180, 0x8000
	v_mov_b32_e32 v181, 0
	v_mov_b32_e32 v196, 0xffff8000
	v_mov_b32_e32 v197, -1
	v_cndmask_b32_e64 v180, v196, v180, s[76:77]
	v_cndmask_b32_e64 v181, v197, v181, s[76:77]
	v_mov_b32_e32 v182, 0x70000
	v_mov_b32_e32 v183, 0
	v_mov_b32_e32 v196, 0xfff90000
	v_cndmask_b32_e64 v182, v196, v182, s[76:77]
	v_cndmask_b32_e64 v183, v197, v183, s[76:77]
	v_and_b32_e32 v186, 7, v184
	v_xor_b32_e32 v186, v185, v186
	v_lshlrev_b32_e32 v186, 4, v186
	v_lshl_or_b32 v178, v184, 7, v186
	v_add_u32_e32 v178, 0x10000, v178
	v_lshrrev_b32_e32 v186, 1, v185
	v_and_b32_e32 v187, 3, v184
	v_xor_b32_e32 v186, v186, v187
	v_lshlrev_b32_e32 v186, 4, v186
	v_and_b32_e32 v187, 1, v185
	v_lshl_or_b32 v186, v187, 3, v186
	v_lshl_or_b32 v179, v184, 6, v186
	v_add_u32_e32 v179, 0x12000, v179
	s_lshl_b32 s0, s11, 10
	s_add_i32 s0, s0, 0x10000
	v_writelane_b32 v246, s0, 20
	s_mov_b32 m0, s0
	s_and_b32 s0, s11, 3
	s_lshl_b32 s0, s0, 10
	s_lshr_b32 s1, s11, 2
	s_lshl_b32 s1, s1, 12
	s_add_i32 s0, s0, s1
	s_add_i32 s0, s0, 0x12000
	v_writelane_b32 v246, s0, 21
	global_load_lds_dwordx4 v[174:175], off
	s_mov_b32 m0, s0
	s_nop 0
	global_load_lds_dwordx4 v[176:177], off
	s_waitcnt vmcnt(0)
	v_readlane_b32 s0, v246, 41
	v_readlane_b32 s1, v246, 42
	v_readlane_b32 s6, v246, 43
	v_readlane_b32 s7, v246, 44
	v_readlane_b32 s8, v246, 45
	v_readlane_b32 s9, v246, 46
	v_readlane_b32 s10, v246, 47
	v_readlane_b32 s11, v246, 48
	s_nop 4
	s_barrier
	v_readlane_b32 s4, v251, 62
	s_branch .LBB0_1361
; __device__ __forceinline__ void gla_unit(LAS unsigned char* lds, const Params& P, const MixBufs& B, float* segst, int layer, int L, int seq, int h, int d, int seg, bool state_only) {
;     ...
;         {
;             const float qf[4] = {__uint_as_float(qr.x << 16), __uint_as_float(qr.x & 0xffff0000u), __uint_as_float(qr.y << 16), __uint_as_float(qr.y & 0xffff0000u)};
;             const float kf[4] = {__uint_as_float(kr.x << 16), __uint_as_float(kr.x & 0xffff0000u), __uint_as_float(kr.y << 16), __uint_as_float(kr.y & 0xffff0000u)};
;             float qd[4], kd[4];
; #pragma unroll
;             for (int kk = 0; kk < 4; ++kk) {
;                 const float b = wave_incl_scan(lv[kk], lane);
;                 const float bl = lane_bcast(b, 63);
;                 blsum[kk] += bl;
;                 qd[kk] = qf[kk] * qscale * __expf(b); kd[kk] = kf[kk] * __expf(-b);
;                 KbT[(4 * w + kk) * C::LT + lane] = (bf16_t)f2bf(kf[kk] * __expf(bl - b));
;                 if (lane == 63) dstate[4 * w + kk] = __expf(bl);
;             }
;             u32x2 o; o.x = pk2(qd[0], qd[1]); o.y = pk2(qd[2], qd[3]); *(LAS u32x2*)(Qa + lane * C::LQ + 4 * w) = o;
;             o.x = pk2(kd[0], kd[1]); o.y = pk2(kd[2], kd[3]); *(LAS u32x2*)(Ka + lane * C::LQ + 4 * w) = o;
;             const unsigned xs[4] = {x0.x, x0.y, x0.z, x0.w};
;             const int rsw = row ^ (part << 3);
; #pragma unroll
;             for (int j = 0; j < 4; ++j) { VT[(part * 8 + 2 * j) * C::LT + rsw] = (bf16_t)(xs[j] & 0xffffu); VT[(part * 8 + 2 * j + 1) * C::LT + rsw] = (bf16_t)(xs[j] >> 16); }
;         }
;         if (c + 1 < cend) GLA_LOAD(c + 1);
;         lds_barrier();
;         if (!state_only) {
; #pragma unroll
;         for (int tt = 0; tt < 2; ++tt) {
;             const int tn = tn0 + tt;
;             f32x4 s = (f32x4){0.f, 0.f, 0.f, 0.f};
;             s = mma_tn_x(s, Qa + tm * 16 * C::LQ, C::LQ, Ka + tn * 16 * C::LQ, C::LQ, 32, lane, 0, 0);
;             const int i = tm * 16 + r, j0 = tn * 16 + q * 4;
;             float v[4];
; #pragma unroll
;             for (int jj = 0; jj < 4; ++jj) { const int j = j0 + jj; const bool on = d == 0 ? (i >= j) : (i > j); v[jj] = on ? s[jj] : 0.f; }
;             u32x2 o; o.x = pk2(v[0], v[1]); o.y = pk2(v[2], v[3]);
;             *(LAS u32x2*)(Sc + i * C::LT + j0) = o;
;         }
;         lds_barrier();
; #pragma unroll
.LBB0_1360:
	s_or_b64 exec, exec, s[0:1]
	v_mul_f32_e32 v57, 0x3fb8aa3b, v24
	v_mul_f32_e32 v24, 0xbfb8aa3b, v24
	v_exp_f32_e32 v24, v24
	v_lshlrev_b32_e32 v25, 16, v19
	v_and_b32_e32 v19, 0xffff0000, v19
	v_mul_f32_e32 v19, 0x3e3504f3, v19
	v_mul_f32_e32 v17, v24, v17
	v_mul_f32_e32 v24, 0x3fb8aa3b, v13
	v_exp_f32_e32 v24, v24
	v_mul_f32_e32 v13, 0xbfb8aa3b, v13
	v_exp_f32_e32 v13, v13
	v_exp_f32_e32 v57, v57
	v_mul_f32_e32 v19, v19, v24
	v_mul_f32_e32 v24, 0x3fb8aa3b, v0
	v_mul_f32_e32 v0, 0xbfb8aa3b, v0
	v_exp_f32_e32 v0, v0
	v_mul_f32_e32 v13, v13, v12
	v_lshlrev_b32_e32 v12, 16, v18
	v_and_b32_e32 v18, 0xffff0000, v18
	v_mul_f32_e32 v0, v0, v15
	v_mul_f32_e32 v15, 0x3e3504f3, v18
	v_mul_f32_e32 v18, 0x3fb8aa3b, v11
	v_mul_f32_e32 v11, 0xbfb8aa3b, v11
	v_exp_f32_e32 v24, v24
	v_exp_f32_e32 v18, v18
	v_exp_f32_e32 v11, v11
	v_mul_f32_e32 v25, 0x3e3504f3, v25
	v_mul_f32_e32 v12, 0x3e3504f3, v12
	v_mul_f32_e32 v25, v25, v57
	v_mul_f32_e32 v12, v12, v24
	v_mul_f32_e32 v15, v15, v18
	v_mul_f32_e32 v18, v11, v10
	v_cvt_pk_bf16_f32 v10, v12, v15
	v_cvt_pk_bf16_f32 v11, v25, v19
	v_cvt_pk_bf16_f32 v12, v0, v18
	v_cvt_pk_bf16_f32 v13, v17, v13
	ds_write2st64_b64 v34, v[10:11], v[12:13] offset1:10
	s_waitcnt vmcnt(0)
	ds_write_b16 v37, v6 offset:14848
	ds_write_b16_d16_hi v37, v6 offset:14992
	ds_write_b16 v37, v7 offset:15136
	ds_write_b16_d16_hi v37, v7 offset:15280
	ds_write_b16 v37, v8 offset:15424
	ds_write_b16_d16_hi v37, v8 offset:15568
	ds_write_b16 v37, v9 offset:15712
	ds_write_b16_d16_hi v37, v9 offset:15856
	v_add_u32_e32 v0, s4, v54
	v_add_u32_e32 v6, s4, v53
	v_cndmask_b32_e64 v6, v6, v0, s[76:77]
	v_ashrrev_i32_e32 v7, 31, v6
	v_lshlrev_b64 v[8:9], 9, v[6:7]
	v_lshl_add_u64 v[8:9], v[20:21], 0, v[8:9]
	v_mad_i64_i32 v[6:7], s[0:1], v6, s65, v[26:27]
	v_add_u32_e32 v0, s4, v52
	v_add_u32_e32 v6, s4, v51
	v_cndmask_b32_e64 v0, v6, v0, s[76:77]
	v_mad_i64_i32 v[6:7], s[0:1], v0, s65, v[28:29]
	global_load_dwordx4 v[6:9], v[6:7], off offset:512
	s_waitcnt lgkmcnt(0)
	s_barrier
	v_lshl_add_u64 v[174:175], v[180:181], 0, v[174:175]
	v_lshl_add_u64 v[176:177], v[182:183], 0, v[176:177]
	v_writelane_b32 v246, s0, 22
	v_readlane_b32 s0, v246, 20
	s_nop 3
	s_mov_b32 m0, s0
	s_nop 0
	global_load_lds_dwordx4 v[174:175], off
	v_readlane_b32 s0, v246, 21
	s_nop 3
	s_mov_b32 m0, s0
	s_nop 0
	global_load_lds_dwordx4 v[176:177], off
	v_readlane_b32 s0, v246, 22
	s_nop 4
	ds_read_b128 v[58:61], v39
	ds_read_b128 v[62:65], v32 offset:5120
	s_waitcnt lgkmcnt(0)
	v_mfma_f32_16x16x32_bf16 v[58:61], v[62:65], v[58:61], 0
	v_readlane_b32 s0, v249, 2
	v_readlane_b32 s1, v249, 3
	s_add_i32 s2, s2, -1
	s_nop 4
	v_cndmask_b32_e32 v0, 0, v58, vcc
	v_cndmask_b32_e64 v15, 0, v59, s[42:43]
	v_cndmask_b32_e64 v17, 0, v60, s[44:45]
	v_cndmask_b32_e64 v57, 0, v61, s[50:51]
	v_cvt_pk_bf16_f32 v58, v0, v15
	v_cvt_pk_bf16_f32 v59, v17, v57
	ds_write_b64 v38, v[58:59] offset:24064
	ds_read_b128 v[58:61], v39
	ds_read_b128 v[62:65], v32 offset:6400
	s_waitcnt lgkmcnt(0)
	v_mfma_f32_16x16x32_bf16 v[58:61], v[62:65], v[58:61], 0
	v_subrev_u32_e32 v51, 64, v51
	v_add_u32_e32 v52, 64, v52
	v_subrev_u32_e32 v53, 64, v53
	s_nop 4
	v_cndmask_b32_e64 v0, 0, v58, s[46:47]
	v_cndmask_b32_e64 v15, 0, v59, s[48:49]
	v_cndmask_b32_e64 v17, 0, v60, s[52:53]
	v_cndmask_b32_e64 v57, 0, v61, s[54:55]
	v_cvt_pk_bf16_f32 v58, v0, v15
	v_cvt_pk_bf16_f32 v59, v17, v57
	ds_write_b64 v41, v[58:59] offset:24064
	s_waitcnt lgkmcnt(0)
	s_barrier
	v_add_u32_e32 v57, v45, v44
	ds_read_b128 v[60:63], v57 offset:24064
	ds_read_b128 v[64:67], v42 offset:14848
	v_add_u32_e32 v58, v45, v49
	ds_read_b128 v[68:71], v58 offset:24064
	ds_read_b128 v[72:75], v40 offset:14848
	s_waitcnt lgkmcnt(2)
	v_mfma_f32_16x16x32_bf16 v[64:67], v[64:67], v[60:63], 0
	v_add_u32_e32 v0, s4, v56
	v_add_u32_e32 v15, s4, v55
	v_mov_b32_e32 v17, v1
	s_waitcnt lgkmcnt(0)
	v_mfma_f32_16x16x32_bf16 v[64:67], v[72:75], v[68:71], v[64:67]
	ds_read_b128 v[72:75], v39
	ds_read_b128 v[76:79], v32 offset:33280
	v_add_u32_e32 v59, v47, v49
	v_add_u32_e32 v54, 64, v54
	s_waitcnt lgkmcnt(0)
	v_mfma_f32_16x16x32_bf16 v[64:67], v[76:79], v[72:75], v[64:67]
	v_cndmask_b32_e64 v76, v0, v15, s[76:77]
	v_ashrrev_i32_e32 v77, 31, v76
	v_lshlrev_b32_e32 v0, 1, v22
	s_nop 4
	v_cvt_pk_bf16_f32 v64, v64, v65
	v_cvt_pk_bf16_f32 v65, v66, v67
	v_lshlrev_b64 v[66:67], 9, v[76:77]
	v_lshl_add_u64 v[76:77], s[0:1], 0, v[66:67]
	v_lshl_add_u64 v[66:67], v[76:77], 0, v[0:1]
	v_mov_b32_e32 v15, v1
	v_lshl_add_u64 v[66:67], v[66:67], 0, v[14:15]
	global_store_dwordx2 v[66:67], v[64:65], off
	ds_read_b128 v[64:67], v36 offset:14848
	s_waitcnt lgkmcnt(0)
	v_mfma_f32_16x16x32_bf16 v[60:63], v[64:67], v[60:63], 0
	ds_read_b128 v[64:67], v35 offset:14848
	v_add_u32_e32 v55, 64, v55
	v_subrev_u32_e32 v56, 64, v56
	s_waitcnt lgkmcnt(0)
	v_mfma_f32_16x16x32_bf16 v[60:63], v[64:67], v[68:71], v[60:63]
	ds_read_b128 v[64:67], v32 offset:34560
	s_cmp_eq_u32 s2, 0
	s_waitcnt lgkmcnt(0)
	v_mfma_f32_16x16x32_bf16 v[60:63], v[64:67], v[72:75], v[60:63]
	s_nop 7
	v_cvt_pk_bf16_f32 v60, v60, v61
	v_cvt_pk_bf16_f32 v61, v62, v63
	v_lshl_add_u64 v[62:63], v[76:77], 0, v[16:17]
	v_lshl_add_u64 v[62:63], v[62:63], 0, v[14:15]
	global_store_dwordx2 v[62:63], v[60:61], off
	v_add_u32_e32 v61, v46, v44
	ds_read_b128 v[62:65], v61 offset:38400
	v_add_u32_e32 v60, v47, v44
	s_waitcnt lgkmcnt(0)
	v_pk_mul_f32 v[2:3], v[2:3], v[62:63]
	v_pk_mul_f32 v[4:5], v[4:5], v[64:65]
	ds_read_b128 v[62:65], v60 offset:10240
	ds_read_b128 v[66:69], v31 offset:14848
	s_waitcnt lgkmcnt(0)
	v_mfma_f32_16x16x32_bf16 v[2:5], v[62:65], v[66:69], v[2:5]
	ds_read_b128 v[62:65], v59 offset:10240
	ds_read_b128 v[66:69], v30 offset:14848
	s_waitcnt vmcnt(2)
	s_waitcnt lgkmcnt(0)
	s_barrier
	s_waitcnt lgkmcnt(0)
	v_mfma_f32_16x16x32_bf16 v[2:5], v[62:65], v[66:69], v[2:5]
	s_nop 7
	v_cvt_pk_bf16_f32 v62, v2, v3
	v_cvt_pk_bf16_f32 v63, v4, v5
	ds_write_b64 v23, v[62:63] offset:33280
	s_cbranch_scc1 .LBB0_1369
; __device__ __forceinline__ unsigned f2bf(float f) { return (unsigned)__builtin_bit_cast(unsigned short, (__bf16)f); }
; __device__ __forceinline__ float lane_bcast(float v, int l) { return __int_as_float(__builtin_amdgcn_readlane(__float_as_int(v), l)); }
; __device__ __forceinline__ void gla_unit(LAS unsigned char* lds, const Params& P, const MixBufs& B, float* segst, int layer, int L, int seq, int h, int d, int seg, bool state_only) {
;     ...
;     for (int c = cbeg; c < cend; ++c) {
;         const int n0 = c * 64;
;         {
;             const float qf[4] = {__uint_as_float(qr.x << 16), __uint_as_float(qr.x & 0xffff0000u), __uint_as_float(qr.y << 16), __uint_as_float(qr.y & 0xffff0000u)};
;             const float kf[4] = {__uint_as_float(kr.x << 16), __uint_as_float(kr.x & 0xffff0000u), __uint_as_float(kr.y << 16), __uint_as_float(kr.y & 0xffff0000u)};
;             float qd[4], kd[4];
; #pragma unroll
;             for (int kk = 0; kk < 4; ++kk) {
;                 const float b = wave_incl_scan(lv[kk], lane);
;                 const float bl = lane_bcast(b, 63);
;                 blsum[kk] += bl;
;                 qd[kk] = qf[kk] * qscale * __expf(b); kd[kk] = kf[kk] * __expf(-b);
;                 KbT[(4 * w + kk) * C::LT + lane] = (bf16_t)f2bf(kf[kk] * __expf(bl - b));
;                 if (lane == 63) dstate[4 * w + kk] = __expf(bl);
.LBB0_1361:
	ds_read_b128 v[10:13], v178
	ds_read_b64 v[18:19], v179
	ds_read_b64 v[24:25], v179 offset:4096
	s_waitcnt lgkmcnt(0)
	s_waitcnt vmcnt(3)
	v_add_f32_dpp v0, v10, v10 row_shr:1 row_mask:0xf bank_mask:0xf bound_ctrl:1
	v_mov_b32_e32 v10, v1
	s_waitcnt vmcnt(1)
	v_lshlrev_b32_e32 v15, 16, v24
	v_add_f32_dpp v0, v0, v0 row_shr:2 row_mask:0xf bank_mask:0xf bound_ctrl:1
	s_nop 1
	v_add_f32_dpp v0, v0, v0 row_shr:4 row_mask:0xf bank_mask:0xf bound_ctrl:1
	s_nop 1
	v_add_f32_dpp v0, v0, v0 row_shr:8 row_mask:0xf bank_mask:0xf bound_ctrl:1
	s_nop 1
	v_mov_b32_dpp v10, v0 row_bcast:15 row_mask:0xa bank_mask:0xf
	v_add_f32_e32 v0, v0, v10
	v_mov_b32_e32 v10, v1
	s_nop 1
	v_mov_b32_dpp v10, v0 row_bcast:31 row_mask:0xc bank_mask:0xf
	v_add_f32_e32 v0, v0, v10
	s_nop 0
	v_readlane_b32 s5, v0, 63
	s_nop 1
	v_sub_f32_e32 v10, s5, v0
	v_mul_f32_e32 v10, 0x3fb8aa3b, v10
	v_exp_f32_e32 v10, v10
	s_nop 0
	v_mul_f32_e32 v10, v10, v15
	v_cvt_pk_bf16_f32 v10, v10, s0
	ds_write_b16 v50, v10 offset:10240
	s_and_saveexec_b64 s[0:1], s[56:57]
	s_cbranch_execz .LBB0_1363
	v_mul_f32_e32 v10, s5, v210
	v_exp_f32_e32 v10, v10
	ds_write_b32 v43, v10 offset:38400

; __device__ __forceinline__ unsigned f2bf(float f) { return (unsigned)__builtin_bit_cast(unsigned short, (__bf16)f); }
; __device__ __forceinline__ float lane_bcast(float v, int l) { return __int_as_float(__builtin_amdgcn_readlane(__float_as_int(v), l)); }
; __device__ __forceinline__ void gla_unit(LAS unsigned char* lds, const Params& P, const MixBufs& B, float* segst, int layer, int L, int seq, int h, int d, int seg, bool state_only) {
;     ...
;     for (int c = cbeg; c < cend; ++c) {
;         const int n0 = c * 64;
;         {
;             const float qf[4] = {__uint_as_float(qr.x << 16), __uint_as_float(qr.x & 0xffff0000u), __uint_as_float(qr.y << 16), __uint_as_float(qr.y & 0xffff0000u)};
;             const float kf[4] = {__uint_as_float(kr.x << 16), __uint_as_float(kr.x & 0xffff0000u), __uint_as_float(kr.y << 16), __uint_as_float(kr.y & 0xffff0000u)};
;             float qd[4], kd[4];
; #pragma unroll
;             for (int kk = 0; kk < 4; ++kk) {
;                 const float b = wave_incl_scan(lv[kk], lane);
;                 const float bl = lane_bcast(b, 63);
;                 blsum[kk] += bl;
;                 qd[kk] = qf[kk] * qscale * __expf(b); kd[kk] = kf[kk] * __expf(-b);
;                 KbT[(4 * w + kk) * C::LT + lane] = (bf16_t)f2bf(kf[kk] * __expf(bl - b));
;                 if (lane == 63) dstate[4 * w + kk] = __expf(bl);
.LBB0_1369:
	ds_read_b128 v[10:13], v178
	ds_read_b64 v[18:19], v179
	ds_read_b64 v[24:25], v179 offset:4096
	s_waitcnt lgkmcnt(0)
	s_waitcnt vmcnt(5)
	v_add_f32_dpp v10, v10, v10 row_shr:1 row_mask:0xf bank_mask:0xf bound_ctrl:1
	v_mov_b32_e32 v15, v1
	s_nop 0
	v_add_f32_dpp v10, v10, v10 row_shr:2 row_mask:0xf bank_mask:0xf bound_ctrl:1
	s_nop 1
	v_add_f32_dpp v10, v10, v10 row_shr:4 row_mask:0xf bank_mask:0xf bound_ctrl:1
	s_nop 1
	v_add_f32_dpp v10, v10, v10 row_shr:8 row_mask:0xf bank_mask:0xf bound_ctrl:1
	s_nop 1
	v_mov_b32_dpp v15, v10 row_bcast:15 row_mask:0xa bank_mask:0xf
	v_add_f32_e32 v10, v10, v15
	v_mov_b32_e32 v15, v1
	s_nop 1
	v_mov_b32_dpp v15, v10 row_bcast:31 row_mask:0xc bank_mask:0xf
	v_add_f32_e32 v10, v10, v15
	s_nop 0
	v_readlane_b32 s2, v10, 63
	s_nop 1
	v_sub_f32_e32 v15, s2, v10
	v_mul_f32_e32 v15, 0x3fb8aa3b, v15
	v_exp_f32_e32 v17, v15
	s_waitcnt vmcnt(3)
	v_lshlrev_b32_e32 v15, 16, v24
	v_mul_f32_e32 v17, v17, v15
	v_cvt_pk_bf16_f32 v17, v17, s0
	ds_write_b16 v50, v17 offset:10240
	s_and_saveexec_b64 s[0:1], s[56:57]
	s_cbranch_execz .LBB0_1371
	v_mul_f32_e32 v17, s2, v210
	v_exp_f32_e32 v17, v17
	ds_write_b32 v43, v17 offset:38400
